# P8 W=2 variant row loop also waits on exact 2-rows-ahead count
# speedup vs baseline: 1.0040x; 1.0003x over previous
; #define LAS __attribute__((address_space(3)))
; __device__ __forceinline__ float bf_lo(unsigned w) { return __uint_as_float(w << 16); }
; __device__ __forceinline__ float bf_hi(unsigned w) { return __uint_as_float(w & 0xffff0000u); }
; #define POOL_LOAD(slot_, r_) do { int e_ = (r_) + HW - 1; e_ = e_ < 0 ? 0 : (e_ > 127 ? 127 : e_); \
;         _Pragma("unroll") for (int j = 0; j < 8; ++j) ring[slot_][j] = *(const GAS unsigned*)(Ub + ((size_t)e_ * 64 + c0 + j) * EI); } while (0)
; template <int W>
; __device__ __forceinline__ void pool_item(const Ctx& F, const bf16* Ub, bf16* Db, int r0, int nr) {
;     ...
;     POOL_LOAD(0, rs); POOL_LOAD(1, rs + 1);
;     __syncthreads();
;     for (int base = rs; base < re; base += NS) {
; #pragma unroll
;         for (int u = 0; u < NS; ++u) {
;             const int r = base + u;
;             if (r < re) {
;                 POOL_LOAD((u + 2) % NS, r + 2);
;                 const int e = r + HW - 1;
;                 const float me = (e >= 0 && e < 128) ? 1.0f : 0.0f, ml = (r >= r0 && r - HW >= 0) ? 1.0f : 0.0f;
; #pragma unroll
;                 for (int j = 0; j < 8; ++j) { Vv[j].x += me * bf_lo(ring[u][j]); Vv[j].y += me * bf_hi(ring[u][j]); }
;                 if (r >= r0) {
;                     LAS f32x2* row = buf + ((r & 1) * 80 + 8) * 64 + lane;
; #pragma unroll
;                     for (int j = 0; j < 8; ++j) row[(c0 + j) * 64] = Vv[j];
;                     asm volatile("s_waitcnt lgkmcnt(0)" ::: "memory"); __builtin_amdgcn_s_barrier(); asm volatile("" ::: "memory");
.LBB0_958:
	s_add_i32 s16, s11, -1
	s_min_i32 s46, s16, 0x7d
	s_ashr_i32 s47, s46, 31
	s_lshl_b64 s[46:47], s[46:47], 20
	v_lshl_add_u64 v[26:27], v[8:9], 0, s[46:47]
	s_mov_b32 s46, 0x200000
	v_add_co_u32_e32 v28, vcc, s46, v26
	s_mov_b32 s46, 0x204000
	s_nop 0
	v_addc_co_u32_e32 v29, vcc, 0, v27, vcc
	v_add_co_u32_e32 v30, vcc, s46, v26
	s_mov_b32 s46, 0x208000
	s_nop 0
	v_addc_co_u32_e32 v31, vcc, 0, v27, vcc
	v_add_co_u32_e32 v32, vcc, s46, v26
	s_mov_b32 s46, 0x20c000
	s_nop 0
	v_addc_co_u32_e32 v33, vcc, 0, v27, vcc
	v_add_co_u32_e32 v34, vcc, s46, v26
	s_mov_b32 s46, 0x210000
	s_nop 0
	v_addc_co_u32_e32 v35, vcc, 0, v27, vcc
	v_add_co_u32_e32 v36, vcc, s46, v26
	s_mov_b32 s46, 0x214000
	s_nop 0
	v_addc_co_u32_e32 v37, vcc, 0, v27, vcc
	v_add_co_u32_e32 v38, vcc, s46, v26
	s_mov_b32 s46, 0x218000
	s_nop 0
	v_addc_co_u32_e32 v39, vcc, 0, v27, vcc
	v_add_co_u32_e32 v40, vcc, s46, v26
	s_mov_b32 s46, 0x21c000
	s_nop 0
	v_addc_co_u32_e32 v41, vcc, 0, v27, vcc
	v_add_co_u32_e32 v26, vcc, s46, v26
	s_cmp_gt_i32 s16, -1
	s_nop 0
	v_addc_co_u32_e32 v27, vcc, 0, v27, vcc
	global_load_dword v127, v[28:29], off
	global_load_dword v126, v[30:31], off
	global_load_dword v125, v[32:33], off
	global_load_dword v124, v[34:35], off
	global_load_dword v123, v[36:37], off
	global_load_dword v122, v[38:39], off
	global_load_dword v121, v[40:41], off
	global_load_dword v120, v[26:27], off
	s_cselect_b64 s[46:47], -1, 0
	v_cndmask_b32_e64 v2, 0, 1.0, s[46:47]
	s_waitcnt vmcnt(23)
	v_lshlrev_b32_e32 v26, 16, v95
	v_and_b32_e32 v27, 0xffff0000, v95
	s_waitcnt vmcnt(22)
	v_lshlrev_b32_e32 v28, 16, v96
	v_and_b32_e32 v29, 0xffff0000, v96
	s_waitcnt vmcnt(21)
	v_lshlrev_b32_e32 v30, 16, v97
	v_and_b32_e32 v31, 0xffff0000, v97
	s_waitcnt vmcnt(20)
	v_lshlrev_b32_e32 v32, 16, v98
	v_and_b32_e32 v33, 0xffff0000, v98
	s_waitcnt vmcnt(19)
	v_lshlrev_b32_e32 v34, 16, v99
	v_and_b32_e32 v35, 0xffff0000, v99
	s_waitcnt vmcnt(18)
	v_lshlrev_b32_e32 v36, 16, v100
	v_and_b32_e32 v37, 0xffff0000, v100
	s_waitcnt vmcnt(17)
	v_lshlrev_b32_e32 v38, 16, v101
	v_and_b32_e32 v39, 0xffff0000, v101
	s_waitcnt vmcnt(16)
	v_lshlrev_b32_e32 v40, 16, v102
	v_and_b32_e32 v41, 0xffff0000, v102
	s_cmp_lt_i32 s16, s10
	v_pk_fma_f32 v[10:11], v[2:3], v[26:27], v[10:11] op_sel_hi:[0,1,1]
	v_pk_fma_f32 v[12:13], v[2:3], v[28:29], v[12:13] op_sel_hi:[0,1,1]
	v_pk_fma_f32 v[14:15], v[2:3], v[30:31], v[14:15] op_sel_hi:[0,1,1]
	v_pk_fma_f32 v[16:17], v[2:3], v[32:33], v[16:17] op_sel_hi:[0,1,1]
	v_pk_fma_f32 v[18:19], v[2:3], v[34:35], v[18:19] op_sel_hi:[0,1,1]
	v_pk_fma_f32 v[20:21], v[2:3], v[36:37], v[20:21] op_sel_hi:[0,1,1]
	v_pk_fma_f32 v[22:23], v[2:3], v[38:39], v[22:23] op_sel_hi:[0,1,1]
	v_pk_fma_f32 v[24:25], v[2:3], v[40:41], v[24:25] op_sel_hi:[0,1,1]
	s_cbranch_scc1 .LBB0_960
	s_max_i32 s50, s44, 1
	s_cmp_gt_i32 s16, 0
	ds_write2st64_b64 v92, v[10:11], v[12:13] offset0:88 offset1:89
	ds_write2st64_b64 v92, v[14:15], v[16:17] offset0:90 offset1:91
	ds_write2st64_b64 v92, v[18:19], v[20:21] offset0:92 offset1:93
	ds_write2st64_b64 v92, v[22:23], v[24:25] offset0:94 offset1:95
	s_cselect_b64 s[46:47], -1, 0
	s_waitcnt lgkmcnt(0)
	s_barrier
; #define GAS __attribute__((address_space(1)))
; __device__ __forceinline__ unsigned cvt_pk_bf16(float lo, float hi) { unsigned r; asm volatile("v_cvt_pk_bf16_f32 %0, %1, %2" : "=v"(r) : "v"(lo), "v"(hi)); return r; }
; __device__ __forceinline__ float bf_lo(unsigned w) { return __uint_as_float(w << 16); }
; __device__ __forceinline__ float bf_hi(unsigned w) { return __uint_as_float(w & 0xffff0000u); }
; template <int W>
; __device__ __forceinline__ void pool_item(const Ctx& F, const bf16* Ub, bf16* Db, int r0, int nr) {
;     ...
;                     const int rlo = r - HW > 0 ? r - HW : 0, rhi = r + HW < 128 ? r + HW : 128; const float icr = 1.0f / (float)(rhi - rlo);
;                     f32x2 h = (f32x2){0.f, 0.f};
; #pragma unroll
;                     for (int c = -HW; c < HW; ++c) h += row[(c0 + c) * 64];
; #pragma unroll
;                     for (int j = 0; j < 8; ++j) {
;                         const float ic = icr * icc[j]; const unsigned m = ring[(u + NS - HW + 1) % NS][j];
;                         *(GAS unsigned*)(Db + ((size_t)r * 64 + c0 + j) * EI) = cvt_pk_bf16(h.x * ic - bf_lo(m), h.y * ic - bf_hi(m));
;                         h += row[(c0 + j + HW) * 64] - row[(c0 + j - HW) * 64];
;                     }
; #pragma unroll
;                     for (int j = 0; j < 8; ++j) { const unsigned l = ring[(u + NS - W + 1) % NS][j]; Vv[j].x -= ml * bf_lo(l); Vv[j].y -= ml * bf_hi(l); }
	v_cndmask_b32_e64 v2, 0, 1.0, s[46:47]
	s_sub_i32 s46, s11, s50
	ds_read2st64_b64 v[42:45], v92 offset0:87 offset1:88
	s_add_i32 s46, s46, 1
	v_cvt_f32_i32_e32 v48, s46
	s_waitcnt lgkmcnt(0)
	v_pk_add_f32 v[42:43], v[42:43], 0 op_sel_hi:[1,0]
	s_nop 0
	v_pk_add_f32 v[46:47], v[42:43], v[44:45]
	v_div_scale_f32 v42, s[46:47], v48, v48, 1.0
	v_rcp_f32_e32 v43, v42
	s_lshl_b64 s[46:47], s[16:17], 20
	v_fma_f32 v44, -v42, v43, 1.0
	v_fmac_f32_e32 v43, v44, v43
	v_div_scale_f32 v44, vcc, 1.0, v48, 1.0
	v_mul_f32_e32 v45, v44, v43
	v_fma_f32 v49, -v42, v45, v44
	v_fmac_f32_e32 v45, v49, v43
	v_fma_f32 v42, -v42, v45, v44
	v_div_fmas_f32 v42, v42, v43, v45
	v_div_fixup_f32 v50, v42, v48, 1.0
	v_mul_f32_e32 v42, v82, v50
	v_fma_f32 v43, v42, v46, -v26
	v_fma_f32 v42, v42, v47, -v27
	v_cvt_pk_bf16_f32 v42, v43, v42
	v_lshl_add_u64 v[48:49], v[6:7], 0, s[46:47]
	global_store_dword v[48:49], v42, off
	ds_read2st64_b64 v[42:45], v92 offset0:87 offset1:89
	s_waitcnt lgkmcnt(0)
	v_pk_add_f32 v[42:43], v[44:45], v[42:43] neg_lo:[0,1] neg_hi:[0,1]
	s_nop 0
	v_pk_add_f32 v[46:47], v[46:47], v[42:43]
	v_mul_f32_e32 v42, v83, v50
	v_fma_f32 v43, v42, v46, -v28
	v_fma_f32 v42, v42, v47, -v29
	v_cvt_pk_bf16_f32 v44, v43, v42
	v_add_co_u32_e32 v42, vcc, s54, v48
	s_nop 1
	v_addc_co_u32_e32 v43, vcc, 0, v49, vcc
	global_store_dword v[42:43], v44, off
	ds_read2st64_b64 v[42:45], v92 offset0:88 offset1:90
	s_waitcnt lgkmcnt(0)
	v_pk_add_f32 v[42:43], v[44:45], v[42:43] neg_lo:[0,1] neg_hi:[0,1]
	s_nop 0
	v_pk_add_f32 v[46:47], v[46:47], v[42:43]
	v_mul_f32_e32 v42, v84, v50
	v_fma_f32 v43, v42, v46, -v30
	v_fma_f32 v42, v42, v47, -v31
	v_cvt_pk_bf16_f32 v44, v43, v42
	v_add_co_u32_e32 v42, vcc, s55, v48
	s_nop 1
	v_addc_co_u32_e32 v43, vcc, 0, v49, vcc
	global_store_dword v[42:43], v44, off
	ds_read2st64_b64 v[42:45], v92 offset0:89 offset1:91
	s_waitcnt lgkmcnt(0)
	v_pk_add_f32 v[42:43], v[44:45], v[42:43] neg_lo:[0,1] neg_hi:[0,1]
	s_nop 0
	v_pk_add_f32 v[46:47], v[46:47], v[42:43]
	v_mul_f32_e32 v42, v85, v50
	v_fma_f32 v43, v42, v46, -v32
	v_fma_f32 v42, v42, v47, -v33
	v_cvt_pk_bf16_f32 v44, v43, v42
	v_add_co_u32_e32 v42, vcc, s56, v48
	s_nop 1
	v_addc_co_u32_e32 v43, vcc, 0, v49, vcc
	global_store_dword v[42:43], v44, off
	ds_read2st64_b64 v[42:45], v92 offset0:90 offset1:92
	s_waitcnt lgkmcnt(0)
	v_pk_add_f32 v[42:43], v[44:45], v[42:43] neg_lo:[0,1] neg_hi:[0,1]
	s_nop 0
	v_pk_add_f32 v[46:47], v[46:47], v[42:43]
	v_mul_f32_e32 v42, v86, v50
	v_fma_f32 v43, v42, v46, -v34
	v_fma_f32 v42, v42, v47, -v35
	v_cvt_pk_bf16_f32 v44, v43, v42
	v_add_co_u32_e32 v42, vcc, s57, v48
	s_nop 1
	v_addc_co_u32_e32 v43, vcc, 0, v49, vcc
	global_store_dword v[42:43], v44, off
	ds_read2st64_b64 v[42:45], v92 offset0:91 offset1:93
	s_waitcnt lgkmcnt(0)
	v_pk_add_f32 v[42:43], v[44:45], v[42:43] neg_lo:[0,1] neg_hi:[0,1]
	s_nop 0
	v_pk_add_f32 v[46:47], v[46:47], v[42:43]
	v_mul_f32_e32 v42, v87, v50
	v_fma_f32 v43, v42, v46, -v36
	v_fma_f32 v42, v42, v47, -v37
	v_cvt_pk_bf16_f32 v44, v43, v42
	v_add_co_u32_e32 v42, vcc, s58, v48
	s_nop 1
	v_addc_co_u32_e32 v43, vcc, 0, v49, vcc
	global_store_dword v[42:43], v44, off
	ds_read2st64_b64 v[42:45], v92 offset0:92 offset1:94
	s_waitcnt lgkmcnt(0)
	v_pk_add_f32 v[42:43], v[44:45], v[42:43] neg_lo:[0,1] neg_hi:[0,1]
	s_nop 0
	v_pk_add_f32 v[46:47], v[46:47], v[42:43]
	v_mul_f32_e32 v42, v88, v50
	v_fma_f32 v43, v42, v46, -v38
	v_fma_f32 v42, v42, v47, -v39
	v_cvt_pk_bf16_f32 v44, v43, v42
	v_add_co_u32_e32 v42, vcc, s59, v48
	s_nop 1
	v_addc_co_u32_e32 v43, vcc, 0, v49, vcc
	global_store_dword v[42:43], v44, off
	ds_read2st64_b64 v[42:45], v92 offset0:93 offset1:95
	s_waitcnt lgkmcnt(0)
	v_pk_add_f32 v[42:43], v[44:45], v[42:43] neg_lo:[0,1] neg_hi:[0,1]
	s_nop 0
	v_pk_add_f32 v[42:43], v[46:47], v[42:43]
	v_mul_f32_e32 v44, v89, v50
	v_fma_f32 v42, v44, v42, -v40
	v_fma_f32 v43, v44, v43, -v41
	v_cvt_pk_bf16_f32 v44, v42, v43
	v_add_co_u32_e32 v42, vcc, s60, v48
	s_nop 1
	v_addc_co_u32_e32 v43, vcc, 0, v49, vcc
	global_store_dword v[42:43], v44, off
	v_lshlrev_b32_e32 v42, 16, v118
	v_and_b32_e32 v43, 0xffff0000, v118
	v_pk_fma_f32 v[10:11], v[2:3], v[42:43], v[10:11] op_sel_hi:[0,1,1] neg_lo:[1,0,0] neg_hi:[1,0,0]
	v_lshlrev_b32_e32 v42, 16, v117
	v_and_b32_e32 v43, 0xffff0000, v117
	v_pk_fma_f32 v[12:13], v[2:3], v[42:43], v[12:13] op_sel_hi:[0,1,1] neg_lo:[1,0,0] neg_hi:[1,0,0]
	v_lshlrev_b32_e32 v42, 16, v116
	v_and_b32_e32 v43, 0xffff0000, v116
	v_pk_fma_f32 v[14:15], v[2:3], v[42:43], v[14:15] op_sel_hi:[0,1,1] neg_lo:[1,0,0] neg_hi:[1,0,0]
	v_lshlrev_b32_e32 v42, 16, v115
	v_and_b32_e32 v43, 0xffff0000, v115
	v_pk_fma_f32 v[16:17], v[2:3], v[42:43], v[16:17] op_sel_hi:[0,1,1] neg_lo:[1,0,0] neg_hi:[1,0,0]
	v_lshlrev_b32_e32 v42, 16, v114
	v_and_b32_e32 v43, 0xffff0000, v114
	v_pk_fma_f32 v[18:19], v[2:3], v[42:43], v[18:19] op_sel_hi:[0,1,1] neg_lo:[1,0,0] neg_hi:[1,0,0]
	v_lshlrev_b32_e32 v42, 16, v113
	v_and_b32_e32 v43, 0xffff0000, v113
	v_pk_fma_f32 v[20:21], v[2:3], v[42:43], v[20:21] op_sel_hi:[0,1,1] neg_lo:[1,0,0] neg_hi:[1,0,0]
	v_lshlrev_b32_e32 v42, 16, v112
	v_and_b32_e32 v43, 0xffff0000, v112
	v_pk_fma_f32 v[22:23], v[2:3], v[42:43], v[22:23] op_sel_hi:[0,1,1] neg_lo:[1,0,0] neg_hi:[1,0,0]
	v_lshlrev_b32_e32 v42, 16, v119
	v_and_b32_e32 v43, 0xffff0000, v119
	v_pk_fma_f32 v[24:25], v[2:3], v[42:43], v[24:25] op_sel_hi:[0,1,1] neg_lo:[1,0,0] neg_hi:[1,0,0]

; #define GAS __attribute__((address_space(1)))
; #define LAS __attribute__((address_space(3)))
; __device__ __forceinline__ unsigned cvt_pk_bf16(float lo, float hi) { unsigned r; asm volatile("v_cvt_pk_bf16_f32 %0, %1, %2" : "=v"(r) : "v"(lo), "v"(hi)); return r; }
; __device__ __forceinline__ float bf_lo(unsigned w) { return __uint_as_float(w << 16); }
; __device__ __forceinline__ float bf_hi(unsigned w) { return __uint_as_float(w & 0xffff0000u); }
; template <int W>
; __device__ __forceinline__ void pool_item(const Ctx& F, const bf16* Ub, bf16* Db, int r0, int nr) {
;     ...
;     POOL_LOAD(0, rs); POOL_LOAD(1, rs + 1);
;     __syncthreads();
;     for (int base = rs; base < re; base += NS) {
; #pragma unroll
;         for (int u = 0; u < NS; ++u) {
;             const int r = base + u;
;             if (r < re) {
;                 POOL_LOAD((u + 2) % NS, r + 2);
;                 const int e = r + HW - 1;
;                 const float me = (e >= 0 && e < 128) ? 1.0f : 0.0f, ml = (r >= r0 && r - HW >= 0) ? 1.0f : 0.0f;
; #pragma unroll
;                 for (int j = 0; j < 8; ++j) { Vv[j].x += me * bf_lo(ring[u][j]); Vv[j].y += me * bf_hi(ring[u][j]); }
;                 if (r >= r0) {
;                     LAS f32x2* row = buf + ((r & 1) * 80 + 8) * 64 + lane;
; #pragma unroll
;                     for (int j = 0; j < 8; ++j) row[(c0 + j) * 64] = Vv[j];
;                     asm volatile("s_waitcnt lgkmcnt(0)" ::: "memory"); __builtin_amdgcn_s_barrier(); asm volatile("" ::: "memory");
;                     const int rlo = r - HW > 0 ? r - HW : 0, rhi = r + HW < 128 ? r + HW : 128; const float icr = 1.0f / (float)(rhi - rlo);
;                     f32x2 h = (f32x2){0.f, 0.f};
; #pragma unroll
;                     for (int c = -HW; c < HW; ++c) h += row[(c0 + c) * 64];
; #pragma unroll
;                     for (int j = 0; j < 8; ++j) {
;                         const float ic = icr * icc[j]; const unsigned m = ring[(u + NS - HW + 1) % NS][j];
;                         *(GAS unsigned*)(Db + ((size_t)r * 64 + c0 + j) * EI) = cvt_pk_bf16(h.x * ic - bf_lo(m), h.y * ic - bf_hi(m));
;                         h += row[(c0 + j + HW) * 64] - row[(c0 + j - HW) * 64];
.LBB0_963:
	s_add_i32 s46, s11, 1
	s_cmp_ge_u32 s46, s45
	s_cbranch_scc1 .LBB0_966
	s_min_i32 s16, s46, 0x7d
	s_add_i32 s16, s16, 2
	s_lshl_b64 s[50:51], s[16:17], 20
	v_lshl_add_u64 v[26:27], v[8:9], 0, s[50:51]
	v_add_co_u32_e32 v28, vcc, 0x4000, v26
	s_cmp_lt_u32 s46, s10
	s_nop 0
	v_addc_co_u32_e32 v29, vcc, 0, v27, vcc
	v_add_co_u32_e32 v30, vcc, 0x8000, v26
	s_nop 1
	v_addc_co_u32_e32 v31, vcc, 0, v27, vcc
	v_add_co_u32_e32 v32, vcc, 0xc000, v26
	s_nop 1
	v_addc_co_u32_e32 v33, vcc, 0, v27, vcc
	v_add_co_u32_e32 v34, vcc, 0x10000, v26
	s_nop 1
	v_addc_co_u32_e32 v35, vcc, 0, v27, vcc
	v_add_co_u32_e32 v36, vcc, 0x14000, v26
	s_nop 1
	v_addc_co_u32_e32 v37, vcc, 0, v27, vcc
	v_add_co_u32_e32 v38, vcc, 0x18000, v26
	s_nop 1
	v_addc_co_u32_e32 v39, vcc, 0, v27, vcc
	v_add_co_u32_e32 v40, vcc, 0x1c000, v26
	s_nop 1
	v_addc_co_u32_e32 v41, vcc, 0, v27, vcc
	global_load_dword v95, v[26:27], off
	global_load_dword v96, v[28:29], off
	global_load_dword v97, v[30:31], off
	global_load_dword v98, v[32:33], off
	global_load_dword v99, v[34:35], off
	global_load_dword v100, v[36:37], off
	global_load_dword v101, v[38:39], off
	global_load_dword v102, v[40:41], off
	s_waitcnt vmcnt(23)
	v_lshlrev_b32_e32 v40, 16, v127
	v_and_b32_e32 v41, 0xffff0000, v127
	s_waitcnt vmcnt(22)
	v_lshlrev_b32_e32 v38, 16, v126
	v_and_b32_e32 v39, 0xffff0000, v126
	s_waitcnt vmcnt(21)
	v_lshlrev_b32_e32 v36, 16, v125
	v_and_b32_e32 v37, 0xffff0000, v125
	s_waitcnt vmcnt(20)
	v_lshlrev_b32_e32 v34, 16, v124
	v_and_b32_e32 v35, 0xffff0000, v124
	s_waitcnt vmcnt(19)
	v_lshlrev_b32_e32 v32, 16, v123
	v_and_b32_e32 v33, 0xffff0000, v123
	s_waitcnt vmcnt(18)
	v_lshlrev_b32_e32 v30, 16, v122
	v_and_b32_e32 v31, 0xffff0000, v122
	s_waitcnt vmcnt(17)
	v_lshlrev_b32_e32 v28, 16, v121
	v_and_b32_e32 v29, 0xffff0000, v121
	s_waitcnt vmcnt(16)
	v_lshlrev_b32_e32 v26, 16, v120
	v_and_b32_e32 v27, 0xffff0000, v120
	v_pk_add_f32 v[10:11], v[10:11], v[40:41]
	v_pk_add_f32 v[12:13], v[12:13], v[38:39]
	v_pk_add_f32 v[14:15], v[14:15], v[36:37]
	v_pk_add_f32 v[16:17], v[16:17], v[34:35]
	v_pk_add_f32 v[18:19], v[18:19], v[32:33]
	v_pk_add_f32 v[20:21], v[20:21], v[30:31]
	v_pk_add_f32 v[22:23], v[22:23], v[28:29]
	v_pk_add_f32 v[24:25], v[24:25], v[26:27]
	s_cbranch_scc1 .LBB0_966
	ds_write2st64_b64 v92, v[10:11], v[12:13] offset0:88 offset1:89
	ds_write2st64_b64 v92, v[14:15], v[16:17] offset0:90 offset1:91
	ds_write2st64_b64 v92, v[18:19], v[20:21] offset0:92 offset1:93
	ds_write2st64_b64 v92, v[22:23], v[24:25] offset0:94 offset1:95
	s_waitcnt lgkmcnt(0)
	s_barrier
	s_min_i32 s16, s22, 0x7f
	ds_read2st64_b64 v[42:45], v92 offset0:87 offset1:88
	s_add_i32 s16, s16, s23
	v_cvt_f32_i32_e32 v2, s16
	s_waitcnt lgkmcnt(0)
	v_pk_add_f32 v[42:43], v[42:43], 0 op_sel_hi:[1,0]
	s_nop 0
	v_pk_add_f32 v[44:45], v[42:43], v[44:45]
	v_div_scale_f32 v42, s[46:47], v2, v2, 1.0
	v_rcp_f32_e32 v43, v42
	s_nop 0
	v_fma_f32 v46, -v42, v43, 1.0
	v_fmac_f32_e32 v43, v46, v43
	v_div_scale_f32 v46, vcc, 1.0, v2, 1.0
	v_mul_f32_e32 v47, v46, v43
	v_fma_f32 v48, -v42, v47, v46
	v_fmac_f32_e32 v47, v48, v43
	v_fma_f32 v42, -v42, v47, v46
	v_div_fmas_f32 v42, v42, v43, v47
	v_div_fixup_f32 v2, v42, v2, 1.0
	v_mul_f32_e32 v42, v82, v2
	v_fma_f32 v40, v42, v44, -v40
	v_lshl_add_u64 v[46:47], v[4:5], 0, s[40:41]
	v_fma_f32 v41, v42, v45, -v41
	v_cvt_pk_bf16_f32 v42, v40, v41
	v_add_co_u32_e32 v40, vcc, s95, v46
	s_nop 1
	v_addc_co_u32_e32 v41, vcc, 0, v47, vcc
	global_store_dword v[40:41], v42, off
	ds_read2st64_b64 v[40:43], v92 offset0:87 offset1:89
	s_waitcnt lgkmcnt(0)
	v_pk_add_f32 v[40:41], v[42:43], v[40:41] neg_lo:[0,1] neg_hi:[0,1]
	s_nop 0
	v_pk_add_f32 v[42:43], v[44:45], v[40:41]
	v_mul_f32_e32 v40, v83, v2
	v_fma_f32 v38, v40, v42, -v38
	v_fma_f32 v39, v40, v43, -v39
	v_cvt_pk_bf16_f32 v40, v38, v39
	v_add_co_u32_e32 v38, vcc, s96, v46
	s_nop 1
	v_addc_co_u32_e32 v39, vcc, 0, v47, vcc
	global_store_dword v[38:39], v40, off
	ds_read2st64_b64 v[38:41], v92 offset0:88 offset1:90
	s_waitcnt lgkmcnt(0)
	v_pk_add_f32 v[38:39], v[40:41], v[38:39] neg_lo:[0,1] neg_hi:[0,1]
	s_nop 0
	v_pk_add_f32 v[40:41], v[42:43], v[38:39]
	v_mul_f32_e32 v38, v84, v2
	v_fma_f32 v36, v38, v40, -v36
	v_fma_f32 v37, v38, v41, -v37
	v_cvt_pk_bf16_f32 v38, v36, v37
	v_add_co_u32_e32 v36, vcc, s97, v46
	s_nop 1
	v_addc_co_u32_e32 v37, vcc, 0, v47, vcc
	global_store_dword v[36:37], v38, off
	ds_read2st64_b64 v[36:39], v92 offset0:89 offset1:91
	s_waitcnt lgkmcnt(0)
	v_pk_add_f32 v[36:37], v[38:39], v[36:37] neg_lo:[0,1] neg_hi:[0,1]
	s_nop 0
	v_pk_add_f32 v[38:39], v[40:41], v[36:37]
	v_mul_f32_e32 v36, v85, v2
	v_fma_f32 v34, v36, v38, -v34
	v_fma_f32 v35, v36, v39, -v35
	v_cvt_pk_bf16_f32 v36, v34, v35
	v_add_co_u32_e32 v34, vcc, s68, v46
	s_nop 1
	v_addc_co_u32_e32 v35, vcc, 0, v47, vcc
	global_store_dword v[34:35], v36, off
	ds_read2st64_b64 v[34:37], v92 offset0:90 offset1:92
	s_waitcnt lgkmcnt(0)
	v_pk_add_f32 v[34:35], v[36:37], v[34:35] neg_lo:[0,1] neg_hi:[0,1]
	s_nop 0
	v_pk_add_f32 v[36:37], v[38:39], v[34:35]
	v_mul_f32_e32 v34, v86, v2
	v_fma_f32 v32, v34, v36, -v32
	v_fma_f32 v33, v34, v37, -v33
	v_cvt_pk_bf16_f32 v34, v32, v33
	v_add_co_u32_e32 v32, vcc, s69, v46
	s_nop 1
	v_addc_co_u32_e32 v33, vcc, 0, v47, vcc
	global_store_dword v[32:33], v34, off
	ds_read2st64_b64 v[32:35], v92 offset0:91 offset1:93
	s_waitcnt lgkmcnt(0)
	v_pk_add_f32 v[32:33], v[34:35], v[32:33] neg_lo:[0,1] neg_hi:[0,1]
	s_nop 0
	v_pk_add_f32 v[34:35], v[36:37], v[32:33]
	v_mul_f32_e32 v32, v87, v2
	v_fma_f32 v30, v32, v34, -v30
	v_fma_f32 v31, v32, v35, -v31
	v_cvt_pk_bf16_f32 v32, v30, v31
	v_add_co_u32_e32 v30, vcc, s13, v46
	s_nop 1
	v_addc_co_u32_e32 v31, vcc, 0, v47, vcc
	global_store_dword v[30:31], v32, off
	ds_read2st64_b64 v[30:33], v92 offset0:92 offset1:94
	s_waitcnt lgkmcnt(0)
; #define GAS __attribute__((address_space(1)))
; #define LAS __attribute__((address_space(3)))
; __device__ __forceinline__ unsigned cvt_pk_bf16(float lo, float hi) { unsigned r; asm volatile("v_cvt_pk_bf16_f32 %0, %1, %2" : "=v"(r) : "v"(lo), "v"(hi)); return r; }
; __device__ __forceinline__ float bf_lo(unsigned w) { return __uint_as_float(w << 16); }
; __device__ __forceinline__ float bf_hi(unsigned w) { return __uint_as_float(w & 0xffff0000u); }
; template <int W>
; __device__ __forceinline__ void pool_item(const Ctx& F, const bf16* Ub, bf16* Db, int r0, int nr) {
;     ...
;     POOL_LOAD(0, rs); POOL_LOAD(1, rs + 1);
;     __syncthreads();
;     for (int base = rs; base < re; base += NS) {
; #pragma unroll
;         for (int u = 0; u < NS; ++u) {
;             const int r = base + u;
;             if (r < re) {
;                 POOL_LOAD((u + 2) % NS, r + 2);
;                 const int e = r + HW - 1;
;                 const float me = (e >= 0 && e < 128) ? 1.0f : 0.0f, ml = (r >= r0 && r - HW >= 0) ? 1.0f : 0.0f;
; #pragma unroll
;                 for (int j = 0; j < 8; ++j) { Vv[j].x += me * bf_lo(ring[u][j]); Vv[j].y += me * bf_hi(ring[u][j]); }
;                 if (r >= r0) {
;                     LAS f32x2* row = buf + ((r & 1) * 80 + 8) * 64 + lane;
; #pragma unroll
;                     for (int j = 0; j < 8; ++j) row[(c0 + j) * 64] = Vv[j];
;                     asm volatile("s_waitcnt lgkmcnt(0)" ::: "memory"); __builtin_amdgcn_s_barrier(); asm volatile("" ::: "memory");
;                     const int rlo = r - HW > 0 ? r - HW : 0, rhi = r + HW < 128 ? r + HW : 128; const float icr = 1.0f / (float)(rhi - rlo);
;                     f32x2 h = (f32x2){0.f, 0.f};
; #pragma unroll
;                     for (int c = -HW; c < HW; ++c) h += row[(c0 + c) * 64];
; #pragma unroll
;                     for (int j = 0; j < 8; ++j) {
;                         const float ic = icr * icc[j]; const unsigned m = ring[(u + NS - HW + 1) % NS][j];
;                         *(GAS unsigned*)(Db + ((size_t)r * 64 + c0 + j) * EI) = cvt_pk_bf16(h.x * ic - bf_lo(m), h.y * ic - bf_hi(m));
;                         h += row[(c0 + j + HW) * 64] - row[(c0 + j - HW) * 64];
;                     }
; #pragma unroll
;                     for (int j = 0; j < 8; ++j) { const unsigned l = ring[(u + NS - W + 1) % NS][j]; Vv[j].x -= ml * bf_lo(l); Vv[j].y -= ml * bf_hi(l); }
	v_pk_add_f32 v[30:31], v[32:33], v[30:31] neg_lo:[0,1] neg_hi:[0,1]
	s_nop 0
	v_pk_add_f32 v[32:33], v[34:35], v[30:31]
	v_mul_f32_e32 v30, v88, v2
	v_fma_f32 v28, v30, v32, -v28
	v_fma_f32 v29, v30, v33, -v29
	v_cvt_pk_bf16_f32 v30, v28, v29
	v_add_co_u32_e32 v28, vcc, s52, v46
	v_mul_f32_e32 v2, v89, v2
	s_nop 0
	v_addc_co_u32_e32 v29, vcc, 0, v47, vcc
	global_store_dword v[28:29], v30, off
	ds_read2st64_b64 v[28:31], v92 offset0:93 offset1:95
	s_waitcnt lgkmcnt(0)
	v_pk_add_f32 v[28:29], v[30:31], v[28:29] neg_lo:[0,1] neg_hi:[0,1]
	s_nop 0
	v_pk_add_f32 v[28:29], v[32:33], v[28:29]
	s_nop 0
	v_fma_f32 v26, v2, v28, -v26
	v_fma_f32 v2, v2, v29, -v27
	v_cvt_pk_bf16_f32 v2, v26, v2
	v_add_co_u32_e32 v26, vcc, s4, v46
	s_nop 1
	v_addc_co_u32_e32 v27, vcc, 0, v47, vcc
	global_store_dword v[26:27], v2, off
	v_lshlrev_b32_e32 v26, 16, v104
	v_and_b32_e32 v27, 0xffff0000, v104
	v_pk_add_f32 v[10:11], v[10:11], v[26:27] neg_lo:[0,1] neg_hi:[0,1]
	v_lshlrev_b32_e32 v26, 16, v105
	v_and_b32_e32 v27, 0xffff0000, v105
	v_pk_add_f32 v[12:13], v[12:13], v[26:27] neg_lo:[0,1] neg_hi:[0,1]
	v_lshlrev_b32_e32 v26, 16, v106
	v_and_b32_e32 v27, 0xffff0000, v106
	v_pk_add_f32 v[14:15], v[14:15], v[26:27] neg_lo:[0,1] neg_hi:[0,1]
	v_lshlrev_b32_e32 v26, 16, v107
	v_and_b32_e32 v27, 0xffff0000, v107
	v_pk_add_f32 v[16:17], v[16:17], v[26:27] neg_lo:[0,1] neg_hi:[0,1]
	v_lshlrev_b32_e32 v26, 16, v108
	v_and_b32_e32 v27, 0xffff0000, v108
	v_pk_add_f32 v[18:19], v[18:19], v[26:27] neg_lo:[0,1] neg_hi:[0,1]
	v_lshlrev_b32_e32 v26, 16, v109
	v_and_b32_e32 v27, 0xffff0000, v109
	v_pk_add_f32 v[20:21], v[20:21], v[26:27] neg_lo:[0,1] neg_hi:[0,1]
	v_lshlrev_b32_e32 v26, 16, v110
	v_and_b32_e32 v27, 0xffff0000, v110
	v_pk_add_f32 v[22:23], v[22:23], v[26:27] neg_lo:[0,1] neg_hi:[0,1]
	v_lshlrev_b32_e32 v26, 16, v111
	v_and_b32_e32 v27, 0xffff0000, v111
	v_pk_add_f32 v[24:25], v[24:25], v[26:27] neg_lo:[0,1] neg_hi:[0,1]
.LBB0_966:
	s_add_i32 s46, s11, 2
	s_cmp_ge_u32 s46, s45
	s_cbranch_scc1 .LBB0_957
	s_min_i32 s16, s46, 0x7d
	s_add_i32 s16, s16, 2
	s_lshl_b64 s[50:51], s[16:17], 20
	v_lshl_add_u64 v[26:27], v[8:9], 0, s[50:51]
	v_add_co_u32_e32 v28, vcc, 0x4000, v26
	s_cmp_lt_u32 s46, s10
	s_nop 0
	v_addc_co_u32_e32 v29, vcc, 0, v27, vcc
	v_add_co_u32_e32 v30, vcc, 0x8000, v26
	s_nop 1
	v_addc_co_u32_e32 v31, vcc, 0, v27, vcc
	v_add_co_u32_e32 v32, vcc, 0xc000, v26
	s_nop 1
	v_addc_co_u32_e32 v33, vcc, 0, v27, vcc
	v_add_co_u32_e32 v34, vcc, 0x10000, v26
	s_nop 1
	v_addc_co_u32_e32 v35, vcc, 0, v27, vcc
	v_add_co_u32_e32 v36, vcc, 0x14000, v26
	s_nop 1
	v_addc_co_u32_e32 v37, vcc, 0, v27, vcc
	v_add_co_u32_e32 v38, vcc, 0x18000, v26
	s_nop 1
	v_addc_co_u32_e32 v39, vcc, 0, v27, vcc
	v_add_co_u32_e32 v40, vcc, 0x1c000, v26
	s_nop 1
	v_addc_co_u32_e32 v41, vcc, 0, v27, vcc
	global_load_dword v104, v[26:27], off
	global_load_dword v105, v[28:29], off
	global_load_dword v106, v[30:31], off
	global_load_dword v107, v[32:33], off
	global_load_dword v108, v[34:35], off
	global_load_dword v109, v[36:37], off
	global_load_dword v110, v[38:39], off
	global_load_dword v111, v[40:41], off
	s_waitcnt vmcnt(23)
	v_lshlrev_b32_e32 v40, 16, v118
	v_and_b32_e32 v41, 0xffff0000, v118
	s_waitcnt vmcnt(22)
	v_lshlrev_b32_e32 v38, 16, v117
	v_and_b32_e32 v39, 0xffff0000, v117
	s_waitcnt vmcnt(21)
	v_lshlrev_b32_e32 v36, 16, v116
	v_and_b32_e32 v37, 0xffff0000, v116
	s_waitcnt vmcnt(20)
	v_lshlrev_b32_e32 v34, 16, v115
	v_and_b32_e32 v35, 0xffff0000, v115
	s_waitcnt vmcnt(19)
	v_lshlrev_b32_e32 v32, 16, v114
	v_and_b32_e32 v33, 0xffff0000, v114
	s_waitcnt vmcnt(18)
	v_lshlrev_b32_e32 v30, 16, v113
	v_and_b32_e32 v31, 0xffff0000, v113
	s_waitcnt vmcnt(17)
	v_lshlrev_b32_e32 v28, 16, v112
	v_and_b32_e32 v29, 0xffff0000, v112
	s_waitcnt vmcnt(16)
	v_lshlrev_b32_e32 v26, 16, v119
	v_and_b32_e32 v27, 0xffff0000, v119
	v_pk_add_f32 v[10:11], v[10:11], v[40:41]
	v_pk_add_f32 v[12:13], v[12:13], v[38:39]
	v_pk_add_f32 v[14:15], v[14:15], v[36:37]
	v_pk_add_f32 v[16:17], v[16:17], v[34:35]
	v_pk_add_f32 v[18:19], v[18:19], v[32:33]
	v_pk_add_f32 v[20:21], v[20:21], v[30:31]
	v_pk_add_f32 v[22:23], v[22:23], v[28:29]
	v_pk_add_f32 v[24:25], v[24:25], v[26:27]
	s_cbranch_scc1 .LBB0_957
	ds_write2st64_b64 v92, v[10:11], v[12:13] offset0:8 offset1:9
	ds_write2st64_b64 v92, v[14:15], v[16:17] offset0:10 offset1:11
	ds_write2st64_b64 v92, v[18:19], v[20:21] offset0:12 offset1:13
	ds_write2st64_b64 v92, v[22:23], v[24:25] offset0:14 offset1:15
	s_waitcnt lgkmcnt(0)
	s_barrier
; #define GAS __attribute__((address_space(1)))
; __device__ __forceinline__ unsigned cvt_pk_bf16(float lo, float hi) { unsigned r; asm volatile("v_cvt_pk_bf16_f32 %0, %1, %2" : "=v"(r) : "v"(lo), "v"(hi)); return r; }
; __device__ __forceinline__ float bf_lo(unsigned w) { return __uint_as_float(w << 16); }
; __device__ __forceinline__ float bf_hi(unsigned w) { return __uint_as_float(w & 0xffff0000u); }
; template <int W>
; __device__ __forceinline__ void pool_item(const Ctx& F, const bf16* Ub, bf16* Db, int r0, int nr) {
;     ...
;                     const int rlo = r - HW > 0 ? r - HW : 0, rhi = r + HW < 128 ? r + HW : 128; const float icr = 1.0f / (float)(rhi - rlo);
;                     f32x2 h = (f32x2){0.f, 0.f};
; #pragma unroll
;                     for (int c = -HW; c < HW; ++c) h += row[(c0 + c) * 64];
; #pragma unroll
;                     for (int j = 0; j < 8; ++j) {
;                         const float ic = icr * icc[j]; const unsigned m = ring[(u + NS - HW + 1) % NS][j];
;                         *(GAS unsigned*)(Db + ((size_t)r * 64 + c0 + j) * EI) = cvt_pk_bf16(h.x * ic - bf_lo(m), h.y * ic - bf_hi(m));
;                         h += row[(c0 + j + HW) * 64] - row[(c0 + j - HW) * 64];
;                     }
; #pragma unroll
;                     for (int j = 0; j < 8; ++j) { const unsigned l = ring[(u + NS - W + 1) % NS][j]; Vv[j].x -= ml * bf_lo(l); Vv[j].y -= ml * bf_hi(l); }
	s_min_i32 s16, s64, 0x7f
	ds_read2st64_b64 v[42:45], v92 offset0:7 offset1:8
	v_add_u32_e32 v2, s16, v103
	v_cvt_f32_i32_e32 v2, v2
	s_waitcnt lgkmcnt(0)
	v_pk_add_f32 v[42:43], v[42:43], 0 op_sel_hi:[1,0]
	s_nop 0
	v_pk_add_f32 v[44:45], v[42:43], v[44:45]
	v_div_scale_f32 v42, s[46:47], v2, v2, 1.0
	v_rcp_f32_e32 v43, v42
	s_nop 0
	v_fma_f32 v46, -v42, v43, 1.0
	v_fmac_f32_e32 v43, v46, v43
	v_div_scale_f32 v46, vcc, 1.0, v2, 1.0
	v_mul_f32_e32 v47, v46, v43
	v_fma_f32 v48, -v42, v47, v46
	v_fmac_f32_e32 v47, v48, v43
	v_fma_f32 v42, -v42, v47, v46
	v_div_fmas_f32 v42, v42, v43, v47
	v_div_fixup_f32 v2, v42, v2, 1.0
	v_mul_f32_e32 v42, v82, v2
	v_fma_f32 v40, v42, v44, -v40
	v_lshl_add_u64 v[46:47], v[4:5], 0, s[40:41]
	v_fma_f32 v41, v42, v45, -v41
	v_cvt_pk_bf16_f32 v42, v40, v41
	v_add_co_u32_e32 v40, vcc, s5, v46
	s_nop 1
	v_addc_co_u32_e32 v41, vcc, 0, v47, vcc
	global_store_dword v[40:41], v42, off
	ds_read2st64_b64 v[40:43], v92 offset0:7 offset1:9
	s_waitcnt lgkmcnt(0)
	v_pk_add_f32 v[40:41], v[42:43], v[40:41] neg_lo:[0,1] neg_hi:[0,1]
	s_nop 0
	v_pk_add_f32 v[42:43], v[44:45], v[40:41]
	v_mul_f32_e32 v40, v83, v2
	v_fma_f32 v38, v40, v42, -v38
	v_fma_f32 v39, v40, v43, -v39
	v_cvt_pk_bf16_f32 v40, v38, v39
	v_add_co_u32_e32 v38, vcc, s6, v46
	s_nop 1
	v_addc_co_u32_e32 v39, vcc, 0, v47, vcc
	global_store_dword v[38:39], v40, off
	ds_read2st64_b64 v[38:41], v92 offset0:8 offset1:10
	s_waitcnt lgkmcnt(0)
	v_pk_add_f32 v[38:39], v[40:41], v[38:39] neg_lo:[0,1] neg_hi:[0,1]
	s_nop 0
	v_pk_add_f32 v[40:41], v[42:43], v[38:39]
	v_mul_f32_e32 v38, v84, v2
	v_fma_f32 v36, v38, v40, -v36
	v_fma_f32 v37, v38, v41, -v37
	v_cvt_pk_bf16_f32 v38, v36, v37
	v_add_co_u32_e32 v36, vcc, s7, v46
	s_nop 1
	v_addc_co_u32_e32 v37, vcc, 0, v47, vcc
	global_store_dword v[36:37], v38, off
	ds_read2st64_b64 v[36:39], v92 offset0:9 offset1:11
	s_waitcnt lgkmcnt(0)
	v_pk_add_f32 v[36:37], v[38:39], v[36:37] neg_lo:[0,1] neg_hi:[0,1]
	s_nop 0
	v_pk_add_f32 v[38:39], v[40:41], v[36:37]
	v_mul_f32_e32 v36, v85, v2
	v_fma_f32 v34, v36, v38, -v34
	v_fma_f32 v35, v36, v39, -v35
	v_cvt_pk_bf16_f32 v36, v34, v35
	v_add_co_u32_e32 v34, vcc, s86, v46
	s_nop 1
	v_addc_co_u32_e32 v35, vcc, 0, v47, vcc
	global_store_dword v[34:35], v36, off
	ds_read2st64_b64 v[34:37], v92 offset0:10 offset1:12
	s_waitcnt lgkmcnt(0)
	v_pk_add_f32 v[34:35], v[36:37], v[34:35] neg_lo:[0,1] neg_hi:[0,1]
	s_nop 0
	v_pk_add_f32 v[36:37], v[38:39], v[34:35]
	v_mul_f32_e32 v34, v86, v2
	v_fma_f32 v32, v34, v36, -v32
	v_fma_f32 v33, v34, v37, -v33
	v_cvt_pk_bf16_f32 v34, v32, v33
	v_add_co_u32_e32 v32, vcc, s34, v46
	s_nop 1
	v_addc_co_u32_e32 v33, vcc, 0, v47, vcc
	global_store_dword v[32:33], v34, off
	ds_read2st64_b64 v[32:35], v92 offset0:11 offset1:13
	s_waitcnt lgkmcnt(0)
	v_pk_add_f32 v[32:33], v[34:35], v[32:33] neg_lo:[0,1] neg_hi:[0,1]
	s_nop 0
	v_pk_add_f32 v[34:35], v[36:37], v[32:33]
	v_mul_f32_e32 v32, v87, v2
	v_fma_f32 v30, v32, v34, -v30
	v_fma_f32 v31, v32, v35, -v31
	v_cvt_pk_bf16_f32 v32, v30, v31
	v_add_co_u32_e32 v30, vcc, s35, v46
	s_nop 1
	v_addc_co_u32_e32 v31, vcc, 0, v47, vcc
	global_store_dword v[30:31], v32, off
	ds_read2st64_b64 v[30:33], v92 offset0:12 offset1:14
	s_waitcnt lgkmcnt(0)
	v_pk_add_f32 v[30:31], v[32:33], v[30:31] neg_lo:[0,1] neg_hi:[0,1]
	s_nop 0
	v_pk_add_f32 v[32:33], v[34:35], v[30:31]
	v_mul_f32_e32 v30, v88, v2
	v_fma_f32 v28, v30, v32, -v28
	v_fma_f32 v29, v30, v33, -v29
	v_cvt_pk_bf16_f32 v30, v28, v29
	v_add_co_u32_e32 v28, vcc, s33, v46
	v_mul_f32_e32 v2, v89, v2
	s_nop 0
	v_addc_co_u32_e32 v29, vcc, 0, v47, vcc
	global_store_dword v[28:29], v30, off
	ds_read2st64_b64 v[28:31], v92 offset0:13 offset1:15
	s_waitcnt lgkmcnt(0)
	v_pk_add_f32 v[28:29], v[30:31], v[28:29] neg_lo:[0,1] neg_hi:[0,1]
	s_nop 0
	v_pk_add_f32 v[28:29], v[32:33], v[28:29]
	s_nop 0
	v_fma_f32 v26, v2, v28, -v26
	v_fma_f32 v2, v2, v29, -v27
	v_cvt_pk_bf16_f32 v2, v26, v2
	v_add_co_u32_e32 v26, vcc, s20, v46
	s_nop 1
	v_addc_co_u32_e32 v27, vcc, 0, v47, vcc
	global_store_dword v[26:27], v2, off
	v_lshlrev_b32_e32 v26, 16, v127
	v_and_b32_e32 v27, 0xffff0000, v127
	v_pk_add_f32 v[10:11], v[10:11], v[26:27] neg_lo:[0,1] neg_hi:[0,1]
	v_lshlrev_b32_e32 v26, 16, v126
	v_and_b32_e32 v27, 0xffff0000, v126
	v_pk_add_f32 v[12:13], v[12:13], v[26:27] neg_lo:[0,1] neg_hi:[0,1]
	v_lshlrev_b32_e32 v26, 16, v125
	v_and_b32_e32 v27, 0xffff0000, v125
	v_pk_add_f32 v[14:15], v[14:15], v[26:27] neg_lo:[0,1] neg_hi:[0,1]
	v_lshlrev_b32_e32 v26, 16, v124
	v_and_b32_e32 v27, 0xffff0000, v124
	v_pk_add_f32 v[16:17], v[16:17], v[26:27] neg_lo:[0,1] neg_hi:[0,1]
	v_lshlrev_b32_e32 v26, 16, v123
	v_and_b32_e32 v27, 0xffff0000, v123
	v_pk_add_f32 v[18:19], v[18:19], v[26:27] neg_lo:[0,1] neg_hi:[0,1]
	v_lshlrev_b32_e32 v26, 16, v122
	v_and_b32_e32 v27, 0xffff0000, v122
	v_pk_add_f32 v[20:21], v[20:21], v[26:27] neg_lo:[0,1] neg_hi:[0,1]
	v_lshlrev_b32_e32 v26, 16, v121
	v_and_b32_e32 v27, 0xffff0000, v121
	v_pk_add_f32 v[22:23], v[22:23], v[26:27] neg_lo:[0,1] neg_hi:[0,1]
	v_lshlrev_b32_e32 v26, 16, v120
	v_and_b32_e32 v27, 0xffff0000, v120
	v_pk_add_f32 v[24:25], v[24:25], v[26:27] neg_lo:[0,1] neg_hi:[0,1]
	s_branch .LBB0_957
